# ERES0/ERES1 row loads marked nt (each line read once)
# speedup vs baseline: 1.0197x; 1.0086x over previous
.LBB0_111:
	s_or_b64 exec, exec, s[44:45]
	v_ashrrev_i32_e32 v67, 31, v66
	s_waitcnt lgkmcnt(0)
	v_lshlrev_b64 v[18:19], 11, v[66:67]
	v_lshl_add_u64 v[68:69], v[60:61], 0, v[18:19]
	v_lshl_add_u64 v[18:19], v[62:63], 0, v[18:19]
	global_load_dwordx4 v[46:49], v[68:69], off nt
	global_load_dwordx4 v[38:41], v[68:69], off offset:1024 nt
	global_load_dwordx4 v[42:45], v[18:19], off nt
	global_load_dwordx4 v[34:37], v[18:19], off offset:1024 nt
	v_add_u32_e32 v64, s16, v66
	v_cmp_gt_i32_e64 s[46:47], s15, v64
	s_nop 1
	v_cndmask_b32_e64 v18, v66, v64, s[46:47]
	v_cmp_lt_i32_e32 vcc, s4, v18
	s_and_saveexec_b64 s[18:19], vcc
	s_xor_b64 s[44:45], exec, s[18:19]
	s_cbranch_execz .LBB0_115
	v_mov_b32_e32 v65, 0
	s_and_saveexec_b64 s[50:51], s[38:39]
	s_cbranch_execz .LBB0_114
	v_lshl_add_u32 v20, v18, 5, v55
	v_mov_b32_e32 v21, v1
	v_lshl_add_u64 v[20:21], v[20:21], 2, s[76:77]
	global_load_dword v65, v[20:21], off

.LBB0_119:
	s_or_b64 exec, exec, s[44:45]
	v_ashrrev_i32_e32 v19, 31, v18
	v_lshlrev_b64 v[18:19], 11, v[18:19]
	v_lshl_add_u64 v[20:21], v[60:61], 0, v[18:19]
	v_lshl_add_u64 v[18:19], v[62:63], 0, v[18:19]
	global_load_dwordx4 v[30:33], v[20:21], off nt
	global_load_dwordx4 v[26:29], v[18:19], off nt
	global_load_dwordx4 v[22:25], v[20:21], off offset:1024 nt
	s_nop 0
	global_load_dwordx4 v[18:21], v[18:19], off offset:1024 nt
	s_waitcnt vmcnt(8)
	ds_bpermute_b32 v51, v72, v50
	s_waitcnt lgkmcnt(0)
	v_add_f32_e32 v50, v50, v51
	ds_bpermute_b32 v51, v73, v50
	s_waitcnt lgkmcnt(0)
	v_add_f32_e32 v50, v50, v51
	ds_bpermute_b32 v51, v74, v50
	s_waitcnt lgkmcnt(0)
	v_add_f32_e32 v50, v50, v51
	ds_bpermute_b32 v51, v75, v50
	s_waitcnt lgkmcnt(0)
	v_add_f32_e32 v50, v50, v51
	ds_bpermute_b32 v51, v76, v50
	s_waitcnt lgkmcnt(0)
	v_add_f32_e32 v50, v50, v51
	ds_bpermute_b32 v51, v77, v50
	s_waitcnt lgkmcnt(0)
	v_add_f32_e32 v50, v50, v51
	v_fmamk_f32 v50, v50, 0x3a800000, v229
	v_cmp_gt_f32_e32 vcc, s5, v50
	v_mul_f32_e32 v51, 0x4f800000, v50
	s_nop 0
	v_cndmask_b32_e32 v50, v50, v51, vcc
	v_sqrt_f32_e32 v51, v50
	s_nop 0
	v_add_u32_e32 v52, -1, v51
	v_fma_f32 v53, -v52, v51, v50
	v_cmp_ge_f32_e64 s[44:45], 0, v53
	v_add_u32_e32 v53, 1, v51
	s_nop 0
	v_cndmask_b32_e64 v52, v51, v52, s[44:45]
	v_fma_f32 v51, -v53, v51, v50
	v_cmp_lt_f32_e64 s[44:45], 0, v51
	s_nop 1
	v_cndmask_b32_e64 v51, v52, v53, s[44:45]
	v_mul_f32_e32 v52, 0x37800000, v51
	v_cndmask_b32_e32 v51, v51, v52, vcc
	v_cmp_class_f32_e32 vcc, v50, v230
	s_mov_b64 s[44:45], -1
	s_nop 0
	v_cndmask_b32_e32 v50, v51, v50, vcc
	v_div_scale_f32 v51, s[18:19], v50, v50, 1.0
	v_rcp_f32_e32 v52, v51
	s_nop 0
	v_fma_f32 v53, -v51, v52, 1.0
	v_fmac_f32_e32 v52, v53, v52
	v_div_scale_f32 v53, vcc, 1.0, v50, 1.0
	v_mul_f32_e32 v70, v53, v52
	v_fma_f32 v71, -v51, v70, v53
	v_fmac_f32_e32 v70, v71, v52
	v_fma_f32 v51, -v51, v70, v53
	v_div_fmas_f32 v51, v51, v52, v70
	v_div_fixup_f32 v70, v51, v50, 1.0
	s_waitcnt vmcnt(5)
	v_lshlrev_b32_e32 v52, 16, v42
	v_and_b32_e32 v53, 0xffff0000, v42
	v_lshlrev_b32_e32 v42, 16, v43
	v_and_b32_e32 v43, 0xffff0000, v43
	v_lshlrev_b32_e32 v50, 16, v46
	v_and_b32_e32 v51, 0xffff0000, v46
	v_pk_mul_f32 v[52:53], v[70:71], v[52:53] op_sel_hi:[0,1]
	v_lshlrev_b32_e32 v46, 16, v47
	v_and_b32_e32 v47, 0xffff0000, v47
	v_pk_mul_f32 v[42:43], v[70:71], v[42:43] op_sel_hi:[0,1]
	v_pk_fma_f32 v[50:51], v[6:7], v[52:53], v[50:51]
	v_pk_fma_f32 v[52:53], v[8:9], v[42:43], v[46:47]
	v_lshlrev_b32_e32 v46, 16, v44
	v_and_b32_e32 v47, 0xffff0000, v44
	v_lshlrev_b32_e32 v42, 16, v48
	v_and_b32_e32 v43, 0xffff0000, v48
	v_pk_mul_f32 v[46:47], v[70:71], v[46:47] op_sel_hi:[0,1]
	v_lshlrev_b32_e32 v44, 16, v45
	v_and_b32_e32 v45, 0xffff0000, v45
	v_pk_fma_f32 v[42:43], v[14:15], v[46:47], v[42:43]
	v_lshlrev_b32_e32 v46, 16, v49
	v_and_b32_e32 v47, 0xffff0000, v49
	v_pk_mul_f32 v[44:45], v[70:71], v[44:45] op_sel_hi:[0,1]
	v_pk_fma_f32 v[44:45], v[16:17], v[44:45], v[46:47]
	s_and_b64 vcc, exec, s[26:27]
	s_cbranch_vccz .LBB0_121
	v_cvt_pk_bf16_f32 v46, v50, v51
	v_cvt_pk_bf16_f32 v47, v52, v53
	v_cvt_pk_bf16_f32 v48, v42, v43
	v_cvt_pk_bf16_f32 v49, v44, v45
	global_store_dwordx4 v[68:69], v[46:49], off
	v_lshlrev_b32_e32 v79, 16, v47
	v_lshlrev_b32_e32 v78, 16, v46
	v_and_b32_e32 v47, 0xffff0000, v47
	v_and_b32_e32 v46, 0xffff0000, v46
	v_pk_mul_f32 v[46:47], v[46:47], v[46:47]
	s_mov_b64 s[44:45], 0
	v_pk_fma_f32 v[46:47], v[78:79], v[78:79], v[46:47]
	v_lshlrev_b32_e32 v79, 16, v49
	v_lshlrev_b32_e32 v78, 16, v48
	v_and_b32_e32 v49, 0xffff0000, v49
	v_and_b32_e32 v48, 0xffff0000, v48
	v_pk_mul_f32 v[48:49], v[48:49], v[48:49]
	v_add_f32_e32 v46, v46, v47
	v_pk_fma_f32 v[48:49], v[78:79], v[78:79], v[48:49]
	s_nop 0
	v_add_f32_e32 v46, v46, v48
	v_add_f32_e32 v48, v46, v49

.LBB0_293:
	s_or_b64 exec, exec, s[44:45]
	v_ashrrev_i32_e32 v59, 31, v58
	s_waitcnt vmcnt(3) lgkmcnt(0)
	v_lshlrev_b64 v[18:19], 11, v[58:59]
	v_lshl_add_u64 v[60:61], v[52:53], 0, v[18:19]
	v_lshl_add_u64 v[18:19], v[54:55], 0, v[18:19]
	global_load_dwordx4 v[42:45], v[60:61], off nt
	global_load_dwordx4 v[34:37], v[60:61], off offset:1024 nt
	global_load_dwordx4 v[46:49], v[18:19], off nt
	global_load_dwordx4 v[38:41], v[18:19], off offset:1024 nt
	v_add_u32_e32 v56, s2, v58
	v_cmp_gt_i32_e64 s[44:45], s49, v56
	s_nop 1
	v_cndmask_b32_e64 v18, v58, v56, s[44:45]
	v_cmp_lt_i32_e32 vcc, s4, v18
	s_and_saveexec_b64 s[16:17], vcc
	s_xor_b64 s[46:47], exec, s[16:17]
	s_cbranch_execz .LBB0_297
	v_mov_b32_e32 v57, 0
	s_and_saveexec_b64 s[68:69], s[38:39]
	s_cbranch_execz .LBB0_296
	v_lshl_add_u32 v20, v18, 5, v62
	v_mov_b32_e32 v21, v1
	v_lshl_add_u64 v[20:21], v[20:21], 2, s[50:51]
	global_load_dword v57, v[20:21], off

.LBB0_301:
	s_or_b64 exec, exec, s[46:47]
	s_waitcnt vmcnt(4)
	ds_bpermute_b32 v70, v63, v69
	v_ashrrev_i32_e32 v19, 31, v18
	v_lshlrev_b64 v[18:19], 11, v[18:19]
	v_lshl_add_u64 v[20:21], v[52:53], 0, v[18:19]
	v_lshl_add_u64 v[22:23], v[54:55], 0, v[18:19]
	s_waitcnt lgkmcnt(0)
	v_add_f32_e32 v69, v69, v70
	ds_bpermute_b32 v70, v64, v69
	global_load_dwordx4 v[26:29], v[20:21], off nt
	global_load_dwordx4 v[30:33], v[22:23], off nt
	s_nop 0
	global_load_dwordx4 v[18:21], v[20:21], off offset:1024 nt
	s_nop 0
	global_load_dwordx4 v[22:25], v[22:23], off offset:1024 nt
	s_waitcnt lgkmcnt(0)
	v_add_f32_e32 v69, v69, v70
	ds_bpermute_b32 v70, v65, v69
	s_waitcnt lgkmcnt(0)
	v_add_f32_e32 v69, v69, v70
	ds_bpermute_b32 v70, v66, v69
	s_waitcnt lgkmcnt(0)
	v_add_f32_e32 v69, v69, v70
	ds_bpermute_b32 v70, v67, v69
	s_waitcnt lgkmcnt(0)
	v_add_f32_e32 v69, v69, v70
	ds_bpermute_b32 v70, v68, v69
	s_waitcnt lgkmcnt(0)
	v_add_f32_e32 v69, v69, v70
	v_fmamk_f32 v69, v69, 0x3a800000, v229
	v_cmp_gt_f32_e32 vcc, s5, v69
	v_mul_f32_e32 v70, 0x4f800000, v69
	s_nop 0
	v_cndmask_b32_e32 v69, v69, v70, vcc
	v_sqrt_f32_e32 v70, v69
	s_nop 0
	v_add_u32_e32 v71, -1, v70
	v_fma_f32 v72, -v71, v70, v69
	v_cmp_ge_f32_e64 s[46:47], 0, v72
	v_add_u32_e32 v72, 1, v70
	s_nop 0
	v_cndmask_b32_e64 v71, v70, v71, s[46:47]
	v_fma_f32 v70, -v72, v70, v69
	v_cmp_lt_f32_e64 s[46:47], 0, v70
	s_nop 1
	v_cndmask_b32_e64 v70, v71, v72, s[46:47]
	v_mul_f32_e32 v71, 0x37800000, v70
	v_cndmask_b32_e32 v70, v70, v71, vcc
	v_cmp_class_f32_e32 vcc, v69, v230
	s_nop 1
	v_cndmask_b32_e32 v69, v70, v69, vcc
	v_div_scale_f32 v70, s[16:17], v69, v69, 1.0
	v_rcp_f32_e32 v71, v70
	s_nop 0
	v_fma_f32 v72, -v70, v71, 1.0
	v_fmac_f32_e32 v71, v72, v71
	v_div_scale_f32 v72, vcc, 1.0, v69, 1.0
	v_mul_f32_e32 v73, v72, v71
	v_fma_f32 v74, -v70, v73, v72
	v_fmac_f32_e32 v73, v74, v71
	v_fma_f32 v70, -v70, v73, v72
	v_div_fmas_f32 v70, v70, v71, v73
	v_div_fixup_f32 v69, v70, v69, 1.0
	s_waitcnt vmcnt(5)
	v_lshlrev_b32_e32 v71, 16, v46
	v_lshlrev_b32_e32 v70, 16, v42
	v_mul_f32_e32 v71, v69, v71
	v_and_b32_e32 v46, 0xffff0000, v46
	v_fmac_f32_e32 v70, v6, v71
	v_and_b32_e32 v42, 0xffff0000, v42
	v_mul_f32_e32 v46, v69, v46
	v_lshlrev_b32_e32 v71, 16, v47
	v_fmac_f32_e32 v42, v7, v46
	v_lshlrev_b32_e32 v46, 16, v43
	v_mul_f32_e32 v71, v69, v71
	v_and_b32_e32 v47, 0xffff0000, v47
	v_fmac_f32_e32 v46, v8, v71
	v_and_b32_e32 v43, 0xffff0000, v43
	v_mul_f32_e32 v47, v69, v47
	v_lshlrev_b32_e32 v71, 16, v48
	v_fmac_f32_e32 v43, v9, v47
	v_lshlrev_b32_e32 v47, 16, v44
	v_mul_f32_e32 v71, v69, v71
	v_and_b32_e32 v48, 0xffff0000, v48
	v_fmac_f32_e32 v47, v14, v71
	v_and_b32_e32 v44, 0xffff0000, v44
	v_mul_f32_e32 v48, v69, v48
	v_lshlrev_b32_e32 v71, 16, v49
	v_and_b32_e32 v49, 0xffff0000, v49
	v_fmac_f32_e32 v44, v15, v48
	v_lshlrev_b32_e32 v48, 16, v45
	v_and_b32_e32 v45, 0xffff0000, v45
	v_mul_f32_e32 v49, v69, v49
	v_mul_f32_e32 v71, v69, v71
	v_fmac_f32_e32 v45, v17, v49
	v_cvt_pk_bf16_f32 v42, v70, v42
	v_fmac_f32_e32 v48, v16, v71
	v_cvt_pk_bf16_f32 v43, v46, v43
	v_cvt_pk_bf16_f32 v44, v47, v44
	v_cvt_pk_bf16_f32 v45, v48, v45
	global_store_dwordx4 v[60:61], v[42:45], off
	v_lshlrev_b32_e32 v46, 16, v42
	s_nop 0
	v_and_b32_e32 v42, 0xffff0000, v42
	v_mul_f32_e32 v42, v42, v42
	v_fmac_f32_e32 v42, v46, v46
	v_lshlrev_b32_e32 v46, 16, v43
	v_and_b32_e32 v43, 0xffff0000, v43
	v_mul_f32_e32 v43, v43, v43
	v_fmac_f32_e32 v43, v46, v46
	v_add_f32_e32 v42, v42, v43
	v_lshlrev_b32_e32 v43, 16, v44
	v_and_b32_e32 v44, 0xffff0000, v44
	v_mul_f32_e32 v44, v44, v44
	v_fmac_f32_e32 v44, v43, v43
	v_add_f32_e32 v42, v42, v44
	v_and_b32_e32 v44, 0xffff0000, v45
	v_lshlrev_b32_e32 v43, 16, v45
	v_mul_f32_e32 v44, v44, v44
	v_fmac_f32_e32 v44, v43, v43
	v_add_f32_e32 v42, v42, v44
	s_waitcnt vmcnt(5)
	v_lshlrev_b32_e32 v44, 16, v38
	v_lshlrev_b32_e32 v43, 16, v34
	v_mul_f32_e32 v44, v69, v44
	v_and_b32_e32 v38, 0xffff0000, v38
	v_fmac_f32_e32 v43, v10, v44
	v_and_b32_e32 v34, 0xffff0000, v34
	v_mul_f32_e32 v38, v69, v38
	v_lshlrev_b32_e32 v44, 16, v39
	v_fmac_f32_e32 v34, v11, v38
	v_lshlrev_b32_e32 v38, 16, v35
	v_mul_f32_e32 v44, v69, v44
	v_and_b32_e32 v39, 0xffff0000, v39
	v_fmac_f32_e32 v38, v12, v44
	v_and_b32_e32 v35, 0xffff0000, v35
	v_mul_f32_e32 v39, v69, v39
	v_lshlrev_b32_e32 v44, 16, v40
	v_fmac_f32_e32 v35, v13, v39
	v_lshlrev_b32_e32 v39, 16, v36
	v_mul_f32_e32 v44, v69, v44
	v_and_b32_e32 v40, 0xffff0000, v40
	v_fmac_f32_e32 v39, v2, v44
	v_and_b32_e32 v36, 0xffff0000, v36
	v_mul_f32_e32 v40, v69, v40
	v_lshlrev_b32_e32 v44, 16, v41
	v_and_b32_e32 v41, 0xffff0000, v41
	v_fmac_f32_e32 v36, v3, v40
	v_lshlrev_b32_e32 v40, 16, v37
	v_and_b32_e32 v37, 0xffff0000, v37
	v_mul_f32_e32 v41, v69, v41
	v_mul_f32_e32 v44, v69, v44
	v_fmac_f32_e32 v37, v5, v41
	v_cvt_pk_bf16_f32 v34, v43, v34
	v_fmac_f32_e32 v40, v4, v44
	v_cvt_pk_bf16_f32 v35, v38, v35
	v_cvt_pk_bf16_f32 v36, v39, v36
	v_cvt_pk_bf16_f32 v37, v40, v37
	global_store_dwordx4 v[60:61], v[34:37], off offset:1024
	v_lshlrev_b32_e32 v38, 16, v34
	s_nop 0
	v_and_b32_e32 v34, 0xffff0000, v34
	v_mul_f32_e32 v34, v34, v34
	v_fmac_f32_e32 v34, v38, v38
	v_lshlrev_b32_e32 v38, 16, v35
	v_and_b32_e32 v35, 0xffff0000, v35
	v_mul_f32_e32 v35, v35, v35
	v_add_f32_e32 v34, v42, v34
	v_fmac_f32_e32 v35, v38, v38
	v_add_f32_e32 v34, v34, v35
	v_lshlrev_b32_e32 v35, 16, v36
	v_and_b32_e32 v36, 0xffff0000, v36
	v_mul_f32_e32 v36, v36, v36
	v_fmac_f32_e32 v36, v35, v35
	v_add_f32_e32 v34, v34, v36
	v_and_b32_e32 v36, 0xffff0000, v37
	v_lshlrev_b32_e32 v35, 16, v37
	v_mul_f32_e32 v36, v36, v36
	v_fmac_f32_e32 v36, v35, v35
	v_add_f32_e32 v34, v34, v36
	ds_bpermute_b32 v35, v63, v34
	s_waitcnt lgkmcnt(0)
	v_add_f32_e32 v34, v34, v35
	ds_bpermute_b32 v35, v64, v34
	s_waitcnt lgkmcnt(0)
	v_add_f32_e32 v34, v34, v35
	ds_bpermute_b32 v35, v65, v34
	s_waitcnt lgkmcnt(0)
	v_add_f32_e32 v34, v34, v35
	ds_bpermute_b32 v35, v66, v34
	s_waitcnt lgkmcnt(0)
	v_add_f32_e32 v34, v34, v35
	ds_bpermute_b32 v35, v67, v34
	s_waitcnt lgkmcnt(0)
	v_add_f32_e32 v34, v34, v35
	ds_bpermute_b32 v35, v68, v34
	s_and_saveexec_b64 s[68:69], s[42:43]
	s_cbranch_execz .LBB0_303
	s_waitcnt lgkmcnt(0)
	v_add_f32_e32 v34, v34, v35
	v_fmamk_f32 v34, v34, 0x3a800000, v229
	v_mul_f32_e32 v35, 0x4f800000, v34
	v_cmp_gt_f32_e32 vcc, s5, v34
	s_nop 1
	v_cndmask_b32_e32 v34, v34, v35, vcc
	v_sqrt_f32_e32 v35, v34
	s_nop 0
	v_add_u32_e32 v36, -1, v35
	v_fma_f32 v38, -v36, v35, v34
	v_add_u32_e32 v37, 1, v35
	v_cmp_ge_f32_e64 s[46:47], 0, v38
	s_nop 1
	v_cndmask_b32_e64 v36, v35, v36, s[46:47]
	v_fma_f32 v35, -v37, v35, v34
	v_cmp_lt_f32_e64 s[46:47], 0, v35
	s_nop 1
	v_cndmask_b32_e64 v35, v36, v37, s[46:47]
	v_mul_f32_e32 v36, 0x37800000, v35
	v_cndmask_b32_e32 v35, v35, v36, vcc
	v_cmp_class_f32_e32 vcc, v34, v230
	s_nop 1
	v_cndmask_b32_e32 v34, v35, v34, vcc
	v_div_scale_f32 v35, s[16:17], v34, v34, 1.0
	v_rcp_f32_e32 v36, v35
	s_nop 0
	v_fma_f32 v37, -v35, v36, 1.0
	v_fmac_f32_e32 v36, v37, v36
	v_div_scale_f32 v37, vcc, 1.0, v34, 1.0
	v_mul_f32_e32 v38, v37, v36
	v_fma_f32 v39, -v35, v38, v37
	v_fmac_f32_e32 v38, v39, v36
	v_fma_f32 v35, -v35, v38, v37
	v_div_fmas_f32 v35, v35, v36, v38
	v_div_fixup_f32 v36, v35, v34, 1.0
	v_lshl_add_u64 v[34:35], v[58:59], 2, s[86:87]
	global_store_dword v[34:35], v36, off
